# norm loop of the post-mix phase: the mid-row waits no longer wait on the next row's prefetch; register rotation and its single counted wait moved to the row end
# speedup vs baseline: 1.0054x; 1.0054x over previous
; __device__ __forceinline__ void norm_phase(const float* lat, const float* ctxp, const bf16_t* dbuf, const bf16_t* dbuf2, const bf16_t* dpart, float* xout, int nrows, const float* gw, const float* mod, int shift_off, int scale_off, bf16_t* outb, float* outf) {
;     const int wid = threadIdx.x >> 6, lane = threadIdx.x & 63;
;     const int nw = gridDim.x * 8, gwv = blockIdx.x * 8 + wid, per = (nrows + nw - 1) / nw;
;     const int rb = gwv * per, re = (rb + per < nrows) ? rb + per : nrows;
;     if (rb >= re) return;
;     int cur_b = -1;
;     f32x4 ca[8], cb[8], v[8]; u32x2 dv[8], dw[8];
;     { const float* src = rb < ML ? lat + (size_t)rb * D : ctxp + (size_t)(rb - ML) * D;
; #pragma unroll
;       for (int i = 0; i < 8; ++i) { v[i] = __builtin_nontemporal_load((const f32x4*)(src + i * 256 + lane * 4)); dv[i] = (u32x2){0u, 0u}; if (dbuf && !dpart) dv[i] = *(const u32x2*)(dbuf + (size_t)rb * D + i * 256 + lane * 4);
;           dw[i] = (u32x2){0u, 0u}; if (dbuf2) dw[i] = __builtin_nontemporal_load((const u32x2*)(dbuf2 + (size_t)rb * D + i * 256 + lane * 4)); } }
.LBB0_1655:
	s_cmp_lt_i32 s76, 12
	s_cselect_b64 s[0:1], -1, 0
	s_cmp_gt_i32 s77, 11
	s_cselect_b64 s[4:5], -1, 0
	s_and_b64 s[0:1], s[0:1], s[4:5]
	s_andn2_b64 vcc, exec, s[0:1]
	s_cbranch_vccnz .LBB0_1717
	s_lshl_b32 s0, s78, 3
	s_abs_i32 s1, s0
	s_waitcnt vmcnt(0)
	v_cvt_f32_u32_e32 v0, s1
	s_add_i32 s3, s0, 0x7fff
	s_sub_i32 s4, 0xffff8001, s0
	s_xor_b32 s0, s3, s0
	v_rcp_iflag_f32_e32 v0, v0
	s_max_i32 s3, s3, s4
	s_sub_i32 s4, 0, s1
	s_ashr_i32 s0, s0, 31
	v_mul_f32_e32 v0, 0x4f7ffffe, v0
	v_cvt_u32_f32_e32 v0, v0
	v_lshl_add_u32 v1, s2, 3, v244
	v_readfirstlane_b32 s5, v0
	s_mul_i32 s4, s4, s5
	s_mul_hi_u32 s4, s5, s4
	s_add_i32 s5, s5, s4
	s_mul_hi_u32 s4, s3, s5
	s_mul_i32 s5, s4, s1
	s_sub_i32 s3, s3, s5
	s_add_i32 s6, s4, 1
	s_sub_i32 s5, s3, s1
	s_cmp_ge_u32 s3, s1
	s_cselect_b32 s4, s6, s4
	s_cselect_b32 s3, s5, s3
	s_add_i32 s5, s4, 1
	s_cmp_ge_u32 s3, s1
	s_cselect_b32 s1, s5, s4
	s_xor_b32 s1, s1, s0
	s_sub_i32 s0, s1, s0
	v_mul_lo_u32 v128, s0, v1
	v_add_u32_e32 v0, s0, v128
	v_min_i32_e32 v196, 0x8000, v0
	v_cmp_lt_i32_e32 vcc, v128, v196
	s_and_saveexec_b64 s[4:5], vcc
	s_cbranch_execz .LBB0_1663
	v_ashrrev_i32_e32 v129, 31, v128
	v_lshlrev_b32_e32 v4, 2, v140
	v_and_b32_e32 v28, 0xfc, v4
	v_mov_b32_e32 v130, 0
	v_lshlrev_b64 v[32:33], 12, v[128:129]
	v_lshl_add_u64 v[4:5], s[74:75], 0, v[32:33]
	v_lshlrev_b32_e32 v6, 1, v28
	v_mov_b32_e32 v7, v130
	v_lshl_add_u64 v[4:5], v[4:5], 0, v[6:7]
	s_mov_b64 s[0:1], 0x32fa4000
	v_lshlrev_b64 v[0:1], 13, v[128:129]
	v_lshl_add_u64 v[34:35], v[4:5], 0, s[0:1]
	s_mov_b32 s0, 0x32fa4000
	v_lshl_add_u64 v[2:3], s[72:73], 0, v[0:1]
	v_lshlrev_b32_e32 v30, 2, v28
	v_mov_b32_e32 v31, v130
	v_add_co_u32_e32 v36, vcc, s0, v4
	v_lshl_add_u64 v[2:3], v[2:3], 0, v[30:31]
	s_nop 0
	v_addc_co_u32_e32 v37, vcc, 0, v5, vcc
	s_movk_i32 s0, 0x1000
	global_load_dwordx4 v[60:63], v[2:3], off nt
	global_load_dwordx4 v[48:51], v[2:3], off offset:1024 nt
	global_load_dwordx4 v[24:27], v[2:3], off offset:2048 nt
	global_load_dwordx4 v[20:23], v[2:3], off offset:3072 nt
	v_add_co_u32_e32 v2, vcc, s0, v2
	v_readlane_b32 s8, v254, 18
	s_nop 0
	v_addc_co_u32_e32 v3, vcc, 0, v3, vcc
	global_load_dwordx2 v[176:177], v[34:35], off offset:512
	global_load_dwordx2 v[174:175], v[34:35], off offset:1024
	global_load_dwordx2 v[172:173], v[34:35], off offset:1536
	global_load_dwordx2 v[170:171], v[34:35], off offset:2048
	global_load_dwordx4 v[16:19], v[2:3], off nt
	global_load_dwordx4 v[12:15], v[2:3], off offset:1024 nt
	global_load_dwordx4 v[8:11], v[2:3], off offset:2048 nt
	global_load_dwordx4 v[4:7], v[2:3], off offset:3072 nt
	global_load_dwordx2 v[178:179], v[36:37], off
	global_load_dwordx2 v[168:169], v[34:35], off offset:2560
	global_load_dwordx2 v[166:167], v[34:35], off offset:3072
	global_load_dwordx2 v[164:165], v[34:35], off offset:3584
	v_mbcnt_lo_u32_b32 v3, -1, 0
	v_readlane_b32 s9, v254, 19
	v_readlane_b32 s16, v254, 26
	v_readlane_b32 s17, v254, 27
	v_mbcnt_hi_u32_b32 v3, -1, v3
	s_mov_b64 s[8:9], s[16:17]
	v_and_b32_e32 v29, 64, v3
	v_lshl_add_u64 v[132:133], s[8:9], 0, v[30:31]
	v_add_u32_e32 v29, 64, v29
	v_xor_b32_e32 v31, 32, v3
	v_cmp_lt_i32_e32 vcc, v31, v29
	v_or_b32_e32 v36, 0x400, v28
	v_lshlrev_b32_e32 v38, 2, v36
	v_cndmask_b32_e32 v31, v3, v31, vcc
	v_lshlrev_b32_e32 v129, 2, v31
	v_xor_b32_e32 v31, 16, v3
	v_cmp_lt_i32_e32 vcc, v31, v29
	v_mov_b32_e32 v39, v130
	v_lshl_add_u64 v[134:135], s[8:9], 0, v[38:39]
	v_cndmask_b32_e32 v31, v3, v31, vcc
	v_lshlrev_b32_e32 v197, 2, v31
	v_xor_b32_e32 v31, 8, v3
	v_cmp_lt_i32_e32 vcc, v31, v29
	v_or_b32_e32 v38, 0x500, v28
	v_lshlrev_b32_e32 v40, 2, v38
	v_cndmask_b32_e32 v31, v3, v31, vcc
	v_lshlrev_b32_e32 v198, 2, v31
	v_xor_b32_e32 v31, 4, v3
	v_cmp_lt_i32_e32 vcc, v31, v29
	v_mov_b32_e32 v41, v130
	v_lshl_add_u64 v[136:137], s[8:9], 0, v[40:41]
	v_cndmask_b32_e32 v31, v3, v31, vcc
	v_lshlrev_b32_e32 v199, 2, v31
	v_xor_b32_e32 v31, 2, v3
	v_cmp_lt_i32_e32 vcc, v31, v29
	v_or_b32_e32 v40, 0x600, v28
	v_lshlrev_b32_e32 v42, 2, v40
	v_cndmask_b32_e32 v31, v3, v31, vcc
	v_lshlrev_b32_e32 v200, 2, v31
	v_xor_b32_e32 v31, 1, v3
	v_cmp_lt_i32_e32 vcc, v31, v29
	v_mov_b32_e32 v43, v130
	v_lshl_add_u64 v[138:139], s[8:9], 0, v[42:43]
	v_cndmask_b32_e32 v3, v3, v31, vcc
	v_or_b32_e32 v42, 0x700, v28
	v_lshlrev_b32_e32 v201, 2, v3
	v_and_b32_e32 v3, 63, v140
	v_lshlrev_b32_e32 v44, 2, v42
	v_mov_b32_e32 v45, v130
	v_lshl_or_b32 v32, v3, 3, v32
	v_lshl_or_b32 v0, v3, 4, v0
	s_add_u32 s6, s74, 0xa100000
	v_readlane_b32 s10, v254, 20
	v_readlane_b32 s11, v254, 21
	v_readlane_b32 s12, v254, 22
	v_readlane_b32 s13, v254, 23
	v_readlane_b32 s14, v254, 24
	v_readlane_b32 s15, v254, 25
	v_readlane_b32 s18, v254, 28
	v_readlane_b32 s19, v254, 29
	v_or_b32_e32 v2, 0x100, v28
	v_or_b32_e32 v30, 0x200, v28
	v_or_b32_e32 v34, 0x300, v28
	v_lshl_add_u64 v[142:143], s[8:9], 0, v[44:45]
	v_lshl_add_u64 v[32:33], s[74:75], 0, v[32:33]
	s_mov_b64 s[0:1], 0x32fa5000
	v_lshl_add_u64 v[0:1], s[72:73], 0, v[0:1]
	s_mov_b64 s[8:9], 0x2000
	s_addc_u32 s7, s75, 0
	v_mov_b32_e32 v149, -1
	v_lshl_add_u64 v[144:145], v[32:33], 0, s[0:1]
	v_lshl_add_u64 v[146:147], v[0:1], 0, s[8:9]
	s_mov_b64 s[10:11], 0
	s_mov_b64 s[12:13], 0xe000
	s_mov_b64 s[14:15], 0xc000
	v_lshlrev_b32_e32 v148, 2, v28
	v_lshlrev_b32_e32 v150, 2, v2
	v_lshlrev_b32_e32 v152, 2, v30
	v_lshlrev_b32_e32 v154, 2, v34
	v_lshlrev_b32_e32 v156, 2, v36
	v_lshlrev_b32_e32 v158, 2, v38
	v_lshlrev_b32_e32 v160, 2, v40
	v_lshlrev_b32_e32 v162, 2, v42
	v_mov_b32_e32 v202, 0x358637bd
	s_mov_b32 s3, 0x800000
	s_mov_b32 s18, 0xd71fd000
	s_mov_b32 s19, 0xd71fe000
	s_mov_b64 s[16:17], 0x1000
	v_readlane_b32 s20, v254, 30
	v_readlane_b32 s21, v254, 31
	v_readlane_b32 s22, v254, 32
	v_readlane_b32 s23, v254, 33
	s_waitcnt vmcnt(0)
	s_branch .LBB0_1659
; __device__ __forceinline__ float bflo(unsigned u) { return __uint_as_float(u << 16); }
; __device__ __forceinline__ float bfhi(unsigned u) { return __uint_as_float(u & 0xffff0000u); }
; __device__ __forceinline__ void norm_phase(const float* lat, const float* ctxp, const bf16_t* dbuf, const bf16_t* dbuf2, const bf16_t* dpart, float* xout, int nrows, const float* gw, const float* mod, int shift_off, int scale_off, bf16_t* outb, float* outf) {
;     ...
;         float ss = 0.f;
; #pragma unroll
;         for (int i = 0; i < 8; ++i) {
;             v[i][0] += bflo(dv[i].x) + bflo(dw[i].x); v[i][1] += bfhi(dv[i].x) + bfhi(dw[i].x); v[i][2] += bflo(dv[i].y) + bflo(dw[i].y); v[i][3] += bfhi(dv[i].y) + bfhi(dw[i].y);
;             ss += v[i][0] * v[i][0] + v[i][1] * v[i][1] + v[i][2] * v[i][2] + v[i][3] * v[i][3]; }
;         ss = wave_sum(ss);
.LBB0_1658:
	s_or_b64 exec, exec, s[0:1]
	v_lshlrev_b32_e32 v212, 16, v170
	v_and_b32_e32 v213, 0xffff0000, v170
	v_lshlrev_b32_e32 v170, 16, v171
	v_and_b32_e32 v171, 0xffff0000, v171
	v_pk_add_f32 v[170:171], v[170:171], 0 op_sel_hi:[1,0]
	v_lshlrev_b32_e32 v204, 16, v178
	v_pk_add_f32 v[18:19], v[170:171], v[18:19]
	v_lshlrev_b32_e32 v170, 16, v168
	v_and_b32_e32 v171, 0xffff0000, v168
	v_and_b32_e32 v205, 0xffff0000, v178
	v_lshlrev_b32_e32 v206, 16, v176
	v_and_b32_e32 v207, 0xffff0000, v176
	v_pk_add_f32 v[212:213], v[212:213], 0 op_sel_hi:[1,0]
	v_pk_add_f32 v[170:171], v[170:171], 0 op_sel_hi:[1,0]
	v_pk_add_f32 v[204:205], v[204:205], 0 op_sel_hi:[1,0]
	v_lshlrev_b32_e32 v178, 16, v179
	v_and_b32_e32 v179, 0xffff0000, v179
	v_pk_add_f32 v[206:207], v[206:207], 0 op_sel_hi:[1,0]
	v_lshlrev_b32_e32 v176, 16, v177
	v_and_b32_e32 v177, 0xffff0000, v177
	v_pk_add_f32 v[16:17], v[212:213], v[16:17]
	v_pk_add_f32 v[12:13], v[170:171], v[12:13]
	v_lshlrev_b32_e32 v168, 16, v169
	v_and_b32_e32 v169, 0xffff0000, v169
	v_pk_add_f32 v[60:61], v[60:61], v[204:205]
	v_pk_add_f32 v[178:179], v[178:179], 0 op_sel_hi:[1,0]
	v_pk_add_f32 v[48:49], v[206:207], v[48:49]
	v_pk_add_f32 v[176:177], v[176:177], 0 op_sel_hi:[1,0]
	v_pk_add_f32 v[168:169], v[168:169], 0 op_sel_hi:[1,0]
	v_mov_b32_e32 v170, v13
	v_mov_b32_e32 v171, v17
	v_pk_add_f32 v[62:63], v[178:179], v[62:63]
	v_pk_mul_f32 v[178:179], v[60:61], v[60:61]
	v_pk_add_f32 v[50:51], v[176:177], v[50:51]
	v_pk_mul_f32 v[176:177], v[48:49], v[48:49]
	v_lshlrev_b32_e32 v208, 16, v174
	v_and_b32_e32 v209, 0xffff0000, v174
	v_pk_add_f32 v[14:15], v[168:169], v[14:15]
	v_mov_b32_e32 v168, v12
	v_mov_b32_e32 v169, v16
	v_pk_mul_f32 v[170:171], v[170:171], v[170:171]
	v_pk_mul_f32 v[204:205], v[62:63], v[62:63]
	v_pk_mul_f32 v[206:207], v[50:51], v[50:51]
	v_pk_add_f32 v[208:209], v[208:209], 0 op_sel_hi:[1,0]
	v_lshlrev_b32_e32 v174, 16, v175
	v_and_b32_e32 v175, 0xffff0000, v175
	v_pk_fma_f32 v[168:169], v[168:169], v[168:169], v[170:171]
	v_mov_b32_e32 v170, v14
	v_mov_b32_e32 v171, v18
	v_add_f32_e32 v131, v176, v177
	v_add_f32_e32 v141, v178, v179
	v_pk_add_f32 v[24:25], v[208:209], v[24:25]
	v_pk_add_f32 v[174:175], v[174:175], 0 op_sel_hi:[1,0]
	v_pk_fma_f32 v[168:169], v[170:171], v[170:171], v[168:169]
	v_mov_b32_e32 v170, v15
	v_mov_b32_e32 v171, v19
	v_add_f32_e32 v131, v206, v131
	v_add_f32_e32 v141, v204, v141
	v_pk_add_f32 v[26:27], v[174:175], v[26:27]
	v_pk_mul_f32 v[174:175], v[24:25], v[24:25]
	v_lshlrev_b32_e32 v210, 16, v172
	v_and_b32_e32 v211, 0xffff0000, v172
	v_pk_fma_f32 v[168:169], v[170:171], v[170:171], v[168:169]
	v_lshlrev_b32_e32 v170, 16, v166
	v_and_b32_e32 v171, 0xffff0000, v166
	v_lshlrev_b32_e32 v166, 16, v167
	v_and_b32_e32 v167, 0xffff0000, v167
	v_add_f32_e32 v131, v207, v131
	v_add_f32_e32 v141, v205, v141
	v_pk_mul_f32 v[208:209], v[26:27], v[26:27]
	v_pk_add_f32 v[210:211], v[210:211], 0 op_sel_hi:[1,0]
	v_lshlrev_b32_e32 v172, 16, v173
	v_and_b32_e32 v173, 0xffff0000, v173
	v_pk_add_f32 v[166:167], v[166:167], 0 op_sel_hi:[1,0]
	v_add_f32_e32 v131, v141, v131
	v_add_f32_e32 v141, v174, v175
	v_pk_add_f32 v[20:21], v[210:211], v[20:21]
	v_pk_add_f32 v[172:173], v[172:173], 0 op_sel_hi:[1,0]
	v_pk_add_f32 v[10:11], v[166:167], v[10:11]
	v_lshlrev_b32_e32 v166, 16, v164
	v_and_b32_e32 v167, 0xffff0000, v164
	v_add_f32_e32 v141, v208, v141
	v_pk_add_f32 v[22:23], v[172:173], v[22:23]
	v_pk_mul_f32 v[172:173], v[20:21], v[20:21]
	v_pk_add_f32 v[170:171], v[170:171], 0 op_sel_hi:[1,0]
	v_pk_add_f32 v[166:167], v[166:167], 0 op_sel_hi:[1,0]
	v_add_f32_e32 v141, v209, v141
	v_pk_mul_f32 v[210:211], v[22:23], v[22:23]
	v_pk_add_f32 v[8:9], v[170:171], v[8:9]
	v_pk_add_f32 v[4:5], v[166:167], v[4:5]
	v_lshlrev_b32_e32 v164, 16, v165
	v_and_b32_e32 v165, 0xffff0000, v165
	v_add_f32_e32 v131, v141, v131
	v_add_f32_e32 v141, v172, v173
	v_pk_add_f32 v[164:165], v[164:165], 0 op_sel_hi:[1,0]
	v_mov_b32_e32 v166, v5
	v_mov_b32_e32 v167, v9
	v_add_f32_e32 v141, v210, v141
	v_pk_add_f32 v[6:7], v[164:165], v[6:7]
	v_mov_b32_e32 v164, v4
	v_mov_b32_e32 v165, v8
	v_pk_mul_f32 v[166:167], v[166:167], v[166:167]
	v_add_f32_e32 v141, v211, v141
	v_pk_fma_f32 v[164:165], v[164:165], v[164:165], v[166:167]
	v_mov_b32_e32 v166, v6
	v_mov_b32_e32 v167, v10
	v_add_f32_e32 v131, v141, v131
	v_pk_fma_f32 v[164:165], v[166:167], v[166:167], v[164:165]
	v_mov_b32_e32 v166, v7
	v_mov_b32_e32 v167, v11
	v_add_f32_e32 v131, v169, v131
	v_pk_fma_f32 v[164:165], v[166:167], v[166:167], v[164:165]
	v_add_f32_e32 v131, v168, v131
	v_add_f32_e32 v131, v165, v131
	v_add_f32_e32 v131, v164, v131
	ds_bpermute_b32 v141, v129, v131
	v_lshl_add_u64 v[146:147], v[146:147], 0, s[8:9]
	s_waitcnt lgkmcnt(0)
	v_add_f32_e32 v131, v131, v141
	ds_bpermute_b32 v141, v197, v131
	s_waitcnt lgkmcnt(0)
	v_add_f32_e32 v131, v131, v141
	ds_bpermute_b32 v141, v198, v131
	s_waitcnt lgkmcnt(0)
	v_add_f32_e32 v131, v131, v141
	ds_bpermute_b32 v141, v199, v131
	s_waitcnt lgkmcnt(0)
	v_add_f32_e32 v131, v131, v141
	ds_bpermute_b32 v141, v200, v131
	s_waitcnt lgkmcnt(0)
	v_add_f32_e32 v131, v131, v141
	ds_bpermute_b32 v141, v201, v131
	s_waitcnt lgkmcnt(0)
; __device__ __forceinline__ unsigned cvt_pk_bf16(float lo, float hi) { unsigned r; asm volatile("v_cvt_pk_bf16_f32 %0, %1, %2" : "=v"(r) : "v"(lo), "v"(hi)); return r; }
; __device__ __forceinline__ void norm_phase(const float* lat, const float* ctxp, const bf16_t* dbuf, const bf16_t* dbuf2, const bf16_t* dpart, float* xout, int nrows, const float* gw, const float* mod, int shift_off, int scale_off, bf16_t* outb, float* outf) {
;     ...
;         const float rstd = rsqrtf(ss * (1.f / 2048.f) + 1e-6f);
; #pragma unroll
;         for (int i = 0; i < 8; ++i) {
;             const int col = i * 256 + lane * 4;
;             if (xout && row < ML) __builtin_nontemporal_store(v[i], (f32x4*)(xout + (size_t)row * D + col));
;             const f32x4 y = v[i] * rstd * ca[i] + cb[i];
;             if (outb) { u32x2 o; o.x = cvt_pk_bf16(y[0], y[1]); o.y = cvt_pk_bf16(y[2], y[3]); *(u32x2*)(outb + (size_t)row * D + col) = o; }
;             else __builtin_nontemporal_store(y, (f32x4*)(outf + (size_t)row * D + col));
;         }
; #pragma unroll
;         for (int i = 0; i < 8; ++i) { v[i] = nv[i]; dv[i] = nd[i]; dw[i] = nw2[i]; }
	v_add_f32_e32 v131, v131, v141
	v_fmamk_f32 v131, v131, 0x3a000000, v202
	v_mul_f32_e32 v141, 0x4b800000, v131
	v_cmp_gt_f32_e32 vcc, s3, v131
	s_nop 1
	v_cndmask_b32_e32 v131, v131, v141, vcc
	v_rsq_f32_e32 v131, v131
	s_nop 0
	v_mul_f32_e32 v141, 0x45800000, v131
	v_cndmask_b32_e32 v164, v131, v141, vcc
	v_pk_mul_f32 v[60:61], v[60:61], v[164:165] op_sel_hi:[1,0]
	v_pk_mul_f32 v[62:63], v[62:63], v[164:165] op_sel_hi:[1,0]
	v_pk_fma_f32 v[60:61], v[64:65], v[60:61], v[0:1]
	v_pk_fma_f32 v[62:63], v[66:67], v[62:63], v[2:3]
	v_cvt_pk_bf16_f32 v60, v60, v61
	v_pk_mul_f32 v[48:49], v[48:49], v[164:165] op_sel_hi:[1,0]
	v_cvt_pk_bf16_f32 v61, v62, v63
	v_add_co_u32_e32 v62, vcc, s18, v144
	v_pk_mul_f32 v[50:51], v[50:51], v[164:165] op_sel_hi:[1,0]
	s_nop 0
	v_addc_co_u32_e32 v63, vcc, -1, v145, vcc
	v_pk_fma_f32 v[50:51], v[70:71], v[50:51], v[30:31]
	v_pk_fma_f32 v[48:49], v[68:69], v[48:49], v[28:29]
	global_store_dwordx2 v[62:63], v[60:61], off
	v_cvt_pk_bf16_f32 v48, v48, v49
	v_cvt_pk_bf16_f32 v49, v50, v51
	v_add_co_u32_e32 v50, vcc, s19, v144
	v_pk_mul_f32 v[24:25], v[24:25], v[164:165] op_sel_hi:[1,0]
	v_pk_mul_f32 v[20:21], v[20:21], v[164:165] op_sel_hi:[1,0]
	v_pk_mul_f32 v[16:17], v[16:17], v[164:165] op_sel_hi:[1,0]
	v_pk_mul_f32 v[12:13], v[12:13], v[164:165] op_sel_hi:[1,0]
	v_pk_mul_f32 v[8:9], v[8:9], v[164:165] op_sel_hi:[1,0]
	v_pk_mul_f32 v[4:5], v[4:5], v[164:165] op_sel_hi:[1,0]
	v_addc_co_u32_e32 v51, vcc, -1, v145, vcc
	v_pk_mul_f32 v[26:27], v[26:27], v[164:165] op_sel_hi:[1,0]
	v_pk_fma_f32 v[24:25], v[72:73], v[24:25], v[32:33]
	v_pk_mul_f32 v[22:23], v[22:23], v[164:165] op_sel_hi:[1,0]
	v_pk_fma_f32 v[20:21], v[76:77], v[20:21], v[36:37]
	v_pk_mul_f32 v[18:19], v[18:19], v[164:165] op_sel_hi:[1,0]
	v_pk_fma_f32 v[16:17], v[80:81], v[16:17], v[40:41]
	v_pk_mul_f32 v[14:15], v[14:15], v[164:165] op_sel_hi:[1,0]
	v_pk_fma_f32 v[12:13], v[84:85], v[12:13], v[44:45]
	v_pk_mul_f32 v[10:11], v[10:11], v[164:165] op_sel_hi:[1,0]
	v_pk_fma_f32 v[8:9], v[88:89], v[8:9], v[52:53]
	v_pk_mul_f32 v[6:7], v[6:7], v[164:165] op_sel_hi:[1,0]
	v_pk_fma_f32 v[4:5], v[92:93], v[4:5], v[56:57]
	global_store_dwordx2 v[50:51], v[48:49], off offset:-3584
	v_pk_fma_f32 v[26:27], v[74:75], v[26:27], v[34:35]
	v_cvt_pk_bf16_f32 v24, v24, v25
	v_pk_fma_f32 v[22:23], v[78:79], v[22:23], v[38:39]
	v_cvt_pk_bf16_f32 v25, v26, v27
	global_store_dwordx2 v[50:51], v[24:25], off offset:-3072
	v_cvt_pk_bf16_f32 v20, v20, v21
	v_cvt_pk_bf16_f32 v21, v22, v23
	global_store_dwordx2 v[50:51], v[20:21], off offset:-2560
	v_pk_fma_f32 v[18:19], v[82:83], v[18:19], v[42:43]
	v_cvt_pk_bf16_f32 v16, v16, v17
	v_pk_fma_f32 v[14:15], v[86:87], v[14:15], v[46:47]
	v_cvt_pk_bf16_f32 v17, v18, v19
	global_store_dwordx2 v[50:51], v[16:17], off offset:-2048
	v_cvt_pk_bf16_f32 v12, v12, v13
	v_cvt_pk_bf16_f32 v13, v14, v15
	global_store_dwordx2 v[50:51], v[12:13], off offset:-1536
	v_pk_fma_f32 v[10:11], v[90:91], v[10:11], v[54:55]
	v_cvt_pk_bf16_f32 v8, v8, v9
	v_pk_fma_f32 v[6:7], v[94:95], v[6:7], v[58:59]
	v_cvt_pk_bf16_f32 v9, v10, v11
	global_store_dwordx2 v[50:51], v[8:9], off offset:-1024
	v_cvt_pk_bf16_f32 v4, v4, v5
	v_cvt_pk_bf16_f32 v5, v6, v7
	global_store_dwordx2 v[50:51], v[4:5], off offset:-512
	v_lshl_add_u64 v[144:145], v[144:145], 0, s[16:17]
	s_waitcnt vmcnt(8)
	v_mov_b64_e32 v[166:167], v[192:193]
	v_mov_b64_e32 v[168:169], v[190:191]
	v_mov_b64_e32 v[170:171], v[188:189]
	v_mov_b64_e32 v[172:173], v[186:187]
	v_mov_b64_e32 v[174:175], v[184:185]
	v_mov_b64_e32 v[176:177], v[182:183]
	v_mov_b64_e32 v[178:179], v[180:181]
	v_mov_b64_e32 v[164:165], v[194:195]
	v_mov_b32_e32 v60, v124
	v_mov_b32_e32 v61, v125
	v_mov_b32_e32 v62, v126
	v_mov_b32_e32 v63, v127
	v_mov_b32_e32 v48, v120
	v_mov_b32_e32 v49, v121
	v_mov_b32_e32 v50, v122
	v_mov_b32_e32 v51, v123
	v_mov_b32_e32 v24, v116
	v_mov_b32_e32 v25, v117
	v_mov_b32_e32 v26, v118
	v_mov_b32_e32 v27, v119
	v_mov_b32_e32 v20, v108
	v_mov_b32_e32 v21, v109
	v_mov_b32_e32 v22, v110
	v_mov_b32_e32 v23, v111
	v_mov_b32_e32 v16, v112
	v_mov_b32_e32 v17, v113
	v_mov_b32_e32 v18, v114
	v_mov_b32_e32 v19, v115
	v_mov_b32_e32 v12, v104
	v_mov_b32_e32 v13, v105
	v_mov_b32_e32 v14, v106
	v_mov_b32_e32 v15, v107
	v_mov_b32_e32 v8, v100
	v_mov_b32_e32 v9, v101
	v_mov_b32_e32 v10, v102
	v_mov_b32_e32 v11, v103
	v_mov_b32_e32 v4, v96
	v_mov_b32_e32 v5, v97
	v_mov_b32_e32 v6, v98
	v_mov_b32_e32 v7, v99
	s_andn2_b64 exec, exec, s[10:11]
	s_cbranch_execz .LBB0_1663
; __device__ __forceinline__ void norm_phase(const float* lat, const float* ctxp, const bf16_t* dbuf, const bf16_t* dbuf2, const bf16_t* dpart, float* xout, int nrows, const float* gw, const float* mod, int shift_off, int scale_off, bf16_t* outb, float* outf) {
;     ...
;         const int b = row < ML ? (row >> 12) : 8;
;         if (b != cur_b) {
;             cur_b = b;
; #pragma unroll
;             for (int i = 0; i < 8; ++i) { const int col = i * 256 + lane * 4; ca[i] = *(const f32x4*)(gw + col); cb[i] = (f32x4){0.f, 0.f, 0.f, 0.f};
;                 if (mod) { const f32x4 sc = *(const f32x4*)(mod + (size_t)b * NMODC + scale_off + col); cb[i] = *(const f32x4*)(mod + (size_t)b * NMODC + shift_off + col); ca[i] = ca[i] * (sc + 1.f); } }
;         }
.LBB0_1659:
	v_min_i32_e32 v96, 0x8000, v128
	v_ashrrev_i32_e32 v96, 12, v96
	v_cmp_ne_u32_e32 vcc, v96, v149
	s_and_saveexec_b64 s[0:1], vcc
	s_cbranch_execz .LBB0_1661
	v_mul_hi_i32_i24_e32 v1, 0x12000, v96
	v_mul_i32_i24_e32 v0, 0x12000, v96
	v_lshl_add_u64 v[0:1], s[6:7], 0, v[0:1]
	v_lshl_add_u64 v[28:29], v[0:1], 0, s[12:13]
	v_lshl_add_u64 v[56:57], v[0:1], 0, s[14:15]
	v_mov_b32_e32 v149, v130
	v_lshl_add_u64 v[30:31], v[28:29], 0, v[148:149]
	v_lshl_add_u64 v[32:33], v[56:57], 0, v[148:149]
	v_mov_b32_e32 v151, v130
	v_mov_b32_e32 v153, v130
	global_load_dwordx4 v[64:67], v[30:31], off
	global_load_dwordx4 v[0:3], v[32:33], off
	global_load_dwordx4 v[68:71], v[132:133], off
	global_load_dwordx4 v[72:75], v[132:133], off offset:1024
	v_lshl_add_u64 v[30:31], v[28:29], 0, v[150:151]
	v_lshl_add_u64 v[32:33], v[28:29], 0, v[152:153]
	v_mov_b32_e32 v155, v130
	global_load_dwordx4 v[76:79], v[30:31], off
	global_load_dwordx4 v[80:83], v[32:33], off
	v_lshl_add_u64 v[32:33], v[28:29], 0, v[154:155]
	v_mov_b32_e32 v157, v130
	global_load_dwordx4 v[84:87], v[32:33], off
	v_lshl_add_u64 v[32:33], v[28:29], 0, v[156:157]
	v_mov_b32_e32 v159, v130
	global_load_dwordx4 v[88:91], v[32:33], off
	v_lshl_add_u64 v[32:33], v[28:29], 0, v[158:159]
	v_mov_b32_e32 v161, v130
	global_load_dwordx4 v[92:95], v[32:33], off
	v_lshl_add_u64 v[32:33], v[28:29], 0, v[160:161]
	v_mov_b32_e32 v163, v130
	v_lshl_add_u64 v[30:31], v[56:57], 0, v[150:151]
	global_load_dwordx4 v[98:101], v[32:33], off
	v_lshl_add_u64 v[28:29], v[28:29], 0, v[162:163]
	v_lshl_add_u64 v[32:33], v[56:57], 0, v[152:153]
	v_lshl_add_u64 v[36:37], v[56:57], 0, v[154:155]
	v_lshl_add_u64 v[40:41], v[56:57], 0, v[156:157]
	v_lshl_add_u64 v[44:45], v[56:57], 0, v[158:159]
	global_load_dwordx4 v[102:105], v[28:29], off
	s_nop 0
	global_load_dwordx4 v[28:31], v[30:31], off
	s_nop 0
	global_load_dwordx4 v[32:35], v[32:33], off
	s_nop 0
	global_load_dwordx4 v[106:109], v[132:133], off offset:2048
	global_load_dwordx4 v[110:113], v[132:133], off offset:3072
	v_lshl_add_u64 v[52:53], v[56:57], 0, v[160:161]
	global_load_dwordx4 v[36:39], v[36:37], off
	s_nop 0
	global_load_dwordx4 v[40:43], v[40:41], off
	s_nop 0
	global_load_dwordx4 v[114:117], v[134:135], off
	global_load_dwordx4 v[118:121], v[136:137], off
	s_nop 0
	global_load_dwordx4 v[44:47], v[44:45], off
	s_nop 0
	global_load_dwordx4 v[122:125], v[138:139], off
	v_lshl_add_u64 v[56:57], v[56:57], 0, v[162:163]
	global_load_dwordx4 v[180:183], v[142:143], off
	s_nop 0
	global_load_dwordx4 v[52:55], v[52:53], off
	v_mov_b32_e32 v149, v96
	global_load_dwordx4 v[56:59], v[56:57], off
	s_waitcnt vmcnt(23)
	v_pk_add_f32 v[66:67], v[66:67], 1.0 op_sel_hi:[1,0]
	v_pk_add_f32 v[64:65], v[64:65], 1.0 op_sel_hi:[1,0]
	s_waitcnt vmcnt(21)
	v_pk_mul_f32 v[66:67], v[70:71], v[66:67]
	v_pk_mul_f32 v[64:65], v[68:69], v[64:65]
	s_waitcnt vmcnt(19)
	v_pk_add_f32 v[78:79], v[78:79], 1.0 op_sel_hi:[1,0]
	v_pk_add_f32 v[76:77], v[76:77], 1.0 op_sel_hi:[1,0]
	s_waitcnt vmcnt(18)
	v_pk_add_f32 v[82:83], v[82:83], 1.0 op_sel_hi:[1,0]
	v_pk_add_f32 v[80:81], v[80:81], 1.0 op_sel_hi:[1,0]
	s_waitcnt vmcnt(17)
	v_pk_add_f32 v[86:87], v[86:87], 1.0 op_sel_hi:[1,0]
	v_pk_add_f32 v[84:85], v[84:85], 1.0 op_sel_hi:[1,0]
	v_pk_mul_f32 v[70:71], v[74:75], v[78:79]
	s_waitcnt vmcnt(16)
	v_pk_add_f32 v[90:91], v[90:91], 1.0 op_sel_hi:[1,0]
	v_pk_add_f32 v[88:89], v[88:89], 1.0 op_sel_hi:[1,0]
	v_pk_mul_f32 v[68:69], v[72:73], v[76:77]
	s_waitcnt vmcnt(15)
	v_pk_add_f32 v[94:95], v[94:95], 1.0 op_sel_hi:[1,0]
	v_pk_add_f32 v[92:93], v[92:93], 1.0 op_sel_hi:[1,0]
	s_waitcnt vmcnt(14)
	v_pk_add_f32 v[100:101], v[100:101], 1.0 op_sel_hi:[1,0]
	v_pk_add_f32 v[98:99], v[98:99], 1.0 op_sel_hi:[1,0]
	s_waitcnt vmcnt(13)
	v_pk_add_f32 v[104:105], v[104:105], 1.0 op_sel_hi:[1,0]
	v_pk_add_f32 v[102:103], v[102:103], 1.0 op_sel_hi:[1,0]
	s_waitcnt vmcnt(10)
	v_pk_mul_f32 v[74:75], v[108:109], v[82:83]
	v_pk_mul_f32 v[72:73], v[106:107], v[80:81]
	s_waitcnt vmcnt(9)
	v_pk_mul_f32 v[78:79], v[112:113], v[86:87]
	v_pk_mul_f32 v[76:77], v[110:111], v[84:85]
	s_waitcnt vmcnt(6)
	v_pk_mul_f32 v[82:83], v[116:117], v[90:91]
	v_pk_mul_f32 v[80:81], v[114:115], v[88:89]
	s_waitcnt vmcnt(5)
	v_pk_mul_f32 v[86:87], v[120:121], v[94:95]
	v_pk_mul_f32 v[84:85], v[118:119], v[92:93]
	s_waitcnt vmcnt(3)
	v_pk_mul_f32 v[90:91], v[124:125], v[100:101]
	v_pk_mul_f32 v[88:89], v[122:123], v[98:99]
	s_waitcnt vmcnt(2)
	v_pk_mul_f32 v[94:95], v[182:183], v[104:105]
	v_pk_mul_f32 v[92:93], v[180:181], v[102:103]
	s_waitcnt vmcnt(0)
